# single-tile workgroups (>=224) of the GQA/SWA in-proj also store q/k/v write-through and skip the barrier's L2 write-back at their early arrival
# baseline (speedup 1.0000x reference)
.LBB0_60:
	s_andn2_saveexec_b64 s[2:3], s[10:11]
	s_cbranch_execz .LBB0_80
	s_mov_b64 s[2:3], exec
	v_readlane_b32 s98, v254, 32
	s_cmp_lt_u32 s98, 224
	s_cbranch_scc1 .Lbar_wb
	s_cmp_eq_u32 s73, 9
	s_cbranch_scc1 .Lbar_nowb
	s_cmp_eq_u32 s73, 14
	s_cbranch_scc1 .Lbar_nowb

.LBB0_424:
	s_cmp_eq_u32 s39, 4
	s_cbranch_scc1 .LBB0_979
	s_cmp_eq_u32 s39, 0
	s_cselect_b64 s[22:23], -1, 0
	s_cmp_gt_i32 s74, 2
	s_cselect_b64 s[4:5], -1, 0
	s_and_b64 s[4:5], s[22:23], s[4:5]
	v_mbcnt_lo_u32_b32 v187, -1, 0
	v_mbcnt_hi_u32_b32 v187, -1, v187
	s_and_b64 vcc, exec, s[4:5]
	v_and_b32_e32 v189, 15, v187
	v_ashrrev_i32_e32 v191, 4, v187
	s_cbranch_vccnz .LBB0_972
	s_cmp_eq_u32 s39, 3
	s_cselect_b64 s[4:5], -1, 0
	s_cmp_gt_i32 s74, 5
	s_cselect_b64 s[6:7], -1, 0
	s_and_b64 s[4:5], s[4:5], s[6:7]
	s_andn2_b64 vcc, exec, s[4:5]
	s_mov_b64 s[4:5], -1
	s_cbranch_vccz .LBB0_972
	s_cmp_lt_i32 s39, 2
	s_cbranch_scc1 .LBB0_687
	s_cmp_gt_i32 s39, 2
	s_cbranch_scc0 .LBB0_639
	v_readlane_b32 s4, v254, 32
	s_cmp_gt_u32 s4, 223
	s_cbranch_scc1 .Lq3w_entry
	s_cmp_lg_u32 s62, 0
	s_cbranch_scc1 .Lq3w_entry
	s_load_dwordx2 s[4:5], s[0:1], 0xd0
	v_readlane_b32 s48, v254, 36
	v_readlane_b32 s49, v254, 45
	v_readlane_b32 s50, v255, 17
	v_readlane_b32 s96, v255, 32
	v_readlane_b32 s97, v255, 33
	v_lshlrev_b32_e32 v131, 7, v189
	v_lshl_add_u32 v131, v191, 4, v131
	v_add_u32_e32 v132, 0x20000, v131
	v_lshlrev_b32_e32 v133, 5, v191
	v_and_b32_e32 v180, 3, v187
	v_lshlrev_b32_e32 v180, 4, v180
	v_lshrrev_b32_e32 v136, 2, v187
	v_add_lshl_u32 v180, v180, v136, 2
	s_lshl_b32 s51, s48, 8
	s_add_u32 s51, s51, s49
	s_sub_u32 s58, s48, 32
	s_and_b32 s59, s58, 3
	s_lshl_b32 s59, s59, 8
	s_add_u32 s59, s59, s49
	s_cmp_gt_u32 s74, 3
	s_cbranch_scc1 .Lq3_kv
	s_lshl_b32 s35, s51, 11
	s_lshl_b32 s70, s74, 9
	s_add_u32 s35, s35, s70
	s_lshl_b32 s70, s19, 1
	s_add_u32 s35, s35, s70
	s_add_u32 s35, s35, 0x3c00000
	s_mov_b32 s33, 0x8000
	s_mov_b32 s34, 0x28000
	s_mov_b32 s36, 0x3e38aa3b
	s_mov_b32 s71, 0xa0
	v_lshrrev_b32_e32 v130, 2, v187
	v_lshlrev_b32_e32 v130, 11, v130
	s_mov_b64 s[24:25], 0
	s_branch .Lq3_common
